# static prio waves 0-3 + attention tile loop: waves 4-7 delayed 512 cycles after each tile barrier (stagger)
# baseline (speedup 1.0000x reference)
; #define SLOAD(t) do { const size_t r0_ = (size_t)((t) * 64 + sr) * LD1 + sc; st_k0 = *(const bf16x8*)(Kh + r0_); st_k1 = *(const bf16x8*)(Kh + r0_ + (size_t)32 * LD1); \
;         st_v0 = *(const bf16x8*)(Vh + r0_); st_v1 = *(const bf16x8*)(Vh + r0_ + (size_t)32 * LD1); } while (0)
; #define SWRITE(bf) do { *(bf16x8*)(K_lds + (bf) * SHM_K + kws) = knorm8(st_k0, kgl + sc); *(bf16x8*)(K_lds + (bf) * SHM_K + kws + 32 * 256) = knorm8(st_k1, kgl + sc); \
;         *(bf16x8*)(V_lds + (bf) * SHM_V + vst0) = st_v0; *(bf16x8*)(V_lds + (bf) * SHM_V + vst1) = st_v1; } while (0)
; template <int BUF>
; __device__ __forceinline__ void fox_tile(f32x16* o, float& m_reg, float& l_reg, const char* lds, const float* ckl, float* al_l, int vb0, const bf16x8* qr, float cq, int qpos, int kb0, bool need_mask, int r32, int hi) {
;     ...
;     for (int r = 0; r < 16; ++r) { p0[r] = __builtin_amdgcn_exp2f(p0[r] - mn); p1[r] = __builtin_amdgcn_exp2f(p1[r] - mn); ps += p0[r] + p1[r]; }
;     { auto rr = __builtin_amdgcn_permlane32_swap(__float_as_uint(ps), __float_as_uint(ps), false, false); ps = __uint_as_float(rr[0]) + __uint_as_float(rr[1]); }
;     l_reg = l_reg * alpha + ps;
; __device__ __forceinline__ void fox_attn_unit(const Params& P, char* lds, int b, int h, int qb) {
;     ...
;     for (int t = NT - 1; t > j_lo; t -= 2) {
;         SLOAD(t - 1);
;         { const int kb0 = t * 64; fox_tile<0>(o, m_reg, l_reg, lds, ckl, al_l, vb0, qr, cq, qpos, kb0, kb0 + 63 > qlo, r32, hi); }
;         SWRITE(1);
;         __syncthreads();
;         if (t - 2 > j_lo) SLOAD(t - 2);
;         { const int kb0 = (t - 1) * 64; fox_tile<1>(o, m_reg, l_reg, lds, ckl, al_l, vb0, qr, cq, qpos, kb0, kb0 + 63 > qlo, r32, hi); }
;         if (t - 2 > j_lo) SWRITE(0);
;         __syncthreads();
;     }
.LBB0_1334:
	v_add_f32_e32 v80, v168, v169
	v_fmac_f32_e32 v80, v156, v167
	v_add_f32_e32 v156, v121, v122
	v_fmac_f32_e32 v156, v80, v120
	v_lshl_add_u64 v[116:117], v[116:117], 0, s[96:97]
	s_add_i32 s6, s6, -2
	v_add_u32_e32 v161, 0x80, v161
	s_addk_i32 s72, 0xff80
	v_add_u32_e32 v162, 0xfffffe00, v162
	v_lshl_add_u64 v[118:119], v[118:119], 0, s[96:97]
	s_and_b64 vcc, exec, s[76:77]
	s_waitcnt lgkmcnt(0)
	s_barrier
	s_nop 0
	v_readfirstlane_b32 s0, v172
	s_nop 0
	s_bitcmp1_b32 s0, 8
	s_cbranch_scc0 .Lstg_0
	s_sleep 8
.Lstg_0:
	s_cbranch_vccnz .LBB0_1351

; __device__ __forceinline__ unsigned cvtpk(float lo, float hi) { f32x2_t v = {lo, hi}; bf16x2_t b = __builtin_convertvector(v, bf16x2_t); return __builtin_bit_cast(unsigned, b); }
; #define PV_RD(S, d0) do { constexpr int b_ = VB * SHM_V + v_rd_off(d0, 0, 0); \
;         TRRD(S##l0, b_); TRRD(S##h0, b_ + 2048); TRRD(S##l1, b_ + 4096); TRRD(S##h1, b_ + 6144); TRRD(S##l2, b_ + 8192); TRRD(S##h2, b_ + 10240); TRRD(S##l3, b_ + 12288); TRRD(S##h3, b_ + 14336); } while (0)
; #define PV_WAIT(n) do { asm volatile("s_waitcnt lgkmcnt(%0)" :: "i"(n) : "memory"); SBAR(); } while (0)
; template <int VB>
; __device__ __forceinline__ void pv_tile(f32x16* o, int vb0, bf16x8 pa0, bf16x8 pa1, bf16x8 pa2, bf16x8 pa3) {
;     ...
;     s16x4 Al0, Al1, Al2, Al3, Ah0, Ah1, Ah2, Ah3, Bl0, Bl1, Bl2, Bl3, Bh0, Bh1, Bh2, Bh3;
;     PV_RD(A, 0); PV_RD(B, 1); PV_WAIT(8); PV_MM(A, 0);
;     PV_RD(A, 2); PV_WAIT(8); PV_MM(B, 1);
;     PV_RD(B, 3); PV_WAIT(8); PV_MM(A, 2);
;     PV_WAIT(0); PV_MM(B, 3);
; __device__ __forceinline__ bf16x8 knorm8(bf16x8 x, const float* g) {
;     const v4u xv = __builtin_bit_cast(v4u, x); float f[8];
; #pragma unroll
;     for (int e = 0; e < 4; ++e) { f[2 * e] = __builtin_bit_cast(float, xv[e] << 16); f[2 * e + 1] = __builtin_bit_cast(float, xv[e] & 0xffff0000u); }
;     float s = 0.f;
; #pragma unroll
;     for (int e = 0; e < 8; ++e) s += f[e] * f[e];
;     s += __shfl_xor(s, 1); s += __shfl_xor(s, 2); s += __shfl_xor(s, 4); s += __shfl_xor(s, 8);
;     const float r = __builtin_amdgcn_rsqf(s * (1.0f / 128.0f) + 1e-6f);
;     const f32x4 g0 = *(const f32x4*)g, g1 = *(const f32x4*)(g + 4);
;     v4u w; w.x = cvtpk(f[0] * r * g0[0], f[1] * r * g0[1]); w.y = cvtpk(f[2] * r * g0[2], f[3] * r * g0[3]); w.z = cvtpk(f[4] * r * g1[0], f[5] * r * g1[1]); w.w = cvtpk(f[6] * r * g1[2], f[7] * r * g1[3]);
;     return __builtin_bit_cast(bf16x8, w);
.LBB0_1341:
	ds_read_b64_tr_b16 v[120:121], v159 offset:0
	ds_read_b64_tr_b16 v[122:123], v159 offset:0x800
	ds_read_b64_tr_b16 v[124:125], v159 offset:0x1000
	ds_read_b64_tr_b16 v[126:127], v159 offset:0x1800
	ds_read_b64_tr_b16 v[130:131], v159 offset:0x2000
	ds_read_b64_tr_b16 v[132:133], v159 offset:0x2800
	ds_read_b64_tr_b16 v[134:135], v159 offset:0x3000
	ds_read_b64_tr_b16 v[136:137], v159 offset:0x3800
	ds_read_b64_tr_b16 v[178:179], v159 offset:0x200
	ds_read_b64_tr_b16 v[180:181], v159 offset:0xa00
	ds_read_b64_tr_b16 v[182:183], v159 offset:0x1200
	ds_read_b64_tr_b16 v[184:185], v159 offset:0x1a00
	ds_read_b64_tr_b16 v[186:187], v159 offset:0x2200
	ds_read_b64_tr_b16 v[188:189], v159 offset:0x2a00
	ds_read_b64_tr_b16 v[190:191], v159 offset:0x3200
	ds_read_b64_tr_b16 v[192:193], v159 offset:0x3a00
	s_waitcnt lgkmcnt(8)
	s_nop 0
	v_mfma_f32_32x32x16_bf16 v[0:15], v[80:83], v[120:123], v[0:15]
	ds_read_b64_tr_b16 v[120:121], v159 offset:0x400
	ds_read_b64_tr_b16 v[122:123], v159 offset:0xc00
	v_mfma_f32_32x32x16_bf16 v[0:15], v[84:87], v[124:127], v[0:15]
	ds_read_b64_tr_b16 v[124:125], v159 offset:0x1400
	ds_read_b64_tr_b16 v[126:127], v159 offset:0x1c00
	v_mfma_f32_32x32x16_bf16 v[0:15], v[88:91], v[130:133], v[0:15]
	ds_read_b64_tr_b16 v[130:131], v159 offset:0x2400
	ds_read_b64_tr_b16 v[132:133], v159 offset:0x2c00
	v_mfma_f32_32x32x16_bf16 v[0:15], v[92:95], v[134:137], v[0:15]
	ds_read_b64_tr_b16 v[134:135], v159 offset:0x3400
	ds_read_b64_tr_b16 v[136:137], v159 offset:0x3c00
	s_waitcnt lgkmcnt(8)
	v_mfma_f32_32x32x16_bf16 v[32:47], v[80:83], v[178:181], v[32:47]
	ds_read_b64_tr_b16 v[178:179], v159 offset:0x600
	ds_read_b64_tr_b16 v[180:181], v159 offset:0xe00
	v_mfma_f32_32x32x16_bf16 v[32:47], v[84:87], v[182:185], v[32:47]
	ds_read_b64_tr_b16 v[182:183], v159 offset:0x1600
	ds_read_b64_tr_b16 v[184:185], v159 offset:0x1e00
	v_mfma_f32_32x32x16_bf16 v[32:47], v[88:91], v[186:189], v[32:47]
	ds_read_b64_tr_b16 v[186:187], v159 offset:0x2600
	ds_read_b64_tr_b16 v[188:189], v159 offset:0x2e00
	v_mfma_f32_32x32x16_bf16 v[32:47], v[92:95], v[190:193], v[32:47]
	ds_read_b64_tr_b16 v[190:191], v159 offset:0x3600
	ds_read_b64_tr_b16 v[192:193], v159 offset:0x3e00
	s_waitcnt lgkmcnt(8)
	v_mfma_f32_32x32x16_bf16 v[48:63], v[80:83], v[120:123], v[48:63]
	s_waitcnt lgkmcnt(0)
	v_mfma_f32_32x32x16_bf16 v[48:63], v[84:87], v[124:127], v[48:63]
	v_mfma_f32_32x32x16_bf16 v[48:63], v[88:91], v[130:133], v[48:63]
	v_mfma_f32_32x32x16_bf16 v[48:63], v[92:95], v[134:137], v[48:63]
	v_mfma_f32_32x32x16_bf16 v[16:31], v[80:83], v[178:181], v[16:31]
	s_waitcnt vmcnt(3)
	v_lshlrev_b32_e32 v124, 16, v108
	v_and_b32_e32 v125, 0xffff0000, v108
	v_lshlrev_b32_e32 v120, 16, v109
	v_and_b32_e32 v121, 0xffff0000, v109
	v_pk_mul_f32 v[126:127], v[124:125], v[124:125]
	v_pk_mul_f32 v[122:123], v[120:121], v[120:121]
	v_add_f32_e32 v126, v126, v127
	v_mfma_f32_32x32x16_bf16 v[16:31], v[84:87], v[182:185], v[16:31]
	v_add_f32_e32 v122, v122, v126
	v_add_f32_e32 v122, v123, v122
	ds_read_b128 v[80:83], v153
	ds_read_b128 v[84:87], v153 offset:16
	s_cmp_gt_i32 s6, s73
	s_cselect_b64 s[78:79], -1, 0
	s_cmp_le_i32 s6, s73
	s_cselect_b64 s[76:77], -1, 0
	v_mfma_f32_32x32x16_bf16 v[16:31], v[88:91], v[186:189], v[16:31]
	v_lshlrev_b32_e32 v88, 16, v111
	v_and_b32_e32 v89, 0xffff0000, v111
	v_mul_f32_e64 v90, v88, v88
	v_mul_f32_e64 v91, v89, v89
	s_and_b64 vcc, exec, s[76:77]
	v_mfma_f32_32x32x16_bf16 v[16:31], v[92:95], v[190:193], v[16:31]
	v_lshlrev_b32_e32 v92, 16, v110
	v_and_b32_e32 v93, 0xffff0000, v110
	v_mul_f32_e64 v94, v92, v92
	v_mul_f32_e64 v95, v93, v93
	v_add_f32_e32 v94, v94, v122
	v_add_f32_e32 v94, v95, v94
	v_add_f32_e32 v90, v90, v94
	v_add_f32_e32 v90, v91, v90
	ds_bpermute_b32 v91, v144, v90
	s_waitcnt lgkmcnt(0)
	v_add_f32_e32 v90, v90, v91
	ds_bpermute_b32 v91, v145, v90
	s_waitcnt lgkmcnt(0)
	v_add_f32_e32 v90, v90, v91
	ds_bpermute_b32 v91, v146, v90
	s_waitcnt lgkmcnt(0)
	v_add_f32_e32 v90, v90, v91
	ds_bpermute_b32 v91, v147, v90
	s_waitcnt lgkmcnt(0)
	v_add_f32_e32 v90, v90, v91
	v_fmamk_f32 v90, v90, 0x3c000000, v141
	v_rsq_f32_e32 v90, v90
	s_nop 0
	v_pk_mul_f32 v[94:95], v[90:91], v[124:125] op_sel_hi:[0,1]
	s_waitcnt vmcnt(2)
	v_lshlrev_b32_e32 v124, 16, v104
	v_and_b32_e32 v125, 0xffff0000, v104
	v_pk_mul_f32 v[80:81], v[80:81], v[94:95]
	v_pk_mul_f32 v[94:95], v[90:91], v[120:121] op_sel_hi:[0,1]
	v_lshlrev_b32_e32 v120, 16, v105
	v_and_b32_e32 v121, 0xffff0000, v105
	v_pk_mul_f32 v[126:127], v[124:125], v[124:125]
	v_pk_mul_f32 v[82:83], v[82:83], v[94:95]
	v_pk_mul_f32 v[122:123], v[120:121], v[120:121]
	v_add_f32_e32 v126, v126, v127
	v_cvt_pk_bf16_f32 v80, v80, v81
	v_cvt_pk_bf16_f32 v81, v82, v83
	v_pk_mul_f32 v[82:83], v[90:91], v[92:93] op_sel_hi:[0,1]
	v_lshlrev_b32_e32 v92, 16, v106
	v_and_b32_e32 v93, 0xffff0000, v106
	v_add_f32_e32 v122, v122, v126
	v_pk_mul_f32 v[94:95], v[92:93], v[92:93]
	v_add_f32_e32 v122, v123, v122
	v_pk_mul_f32 v[82:83], v[84:85], v[82:83]
	v_pk_mul_f32 v[84:85], v[90:91], v[88:89] op_sel_hi:[0,1]
	v_lshlrev_b32_e32 v88, 16, v107
	v_and_b32_e32 v89, 0xffff0000, v107
	v_add_f32_e32 v94, v94, v122
	v_pk_mul_f32 v[90:91], v[88:89], v[88:89]
	v_add_f32_e32 v94, v95, v94
	v_add_f32_e32 v90, v90, v94
	v_add_f32_e32 v90, v91, v90
	ds_bpermute_b32 v91, v144, v90
	v_pk_mul_f32 v[84:85], v[86:87], v[84:85]
	v_cvt_pk_bf16_f32 v82, v82, v83
	v_cvt_pk_bf16_f32 v83, v84, v85
	ds_write_b128 v154, v[80:83] offset:49152
	s_waitcnt lgkmcnt(1)
	v_add_f32_e32 v90, v90, v91
	ds_bpermute_b32 v91, v145, v90
	ds_read_b128 v[80:83], v153
	ds_read_b128 v[84:87], v153 offset:16
	s_waitcnt lgkmcnt(2)
	v_add_f32_e32 v90, v90, v91
	ds_bpermute_b32 v91, v146, v90
	s_waitcnt lgkmcnt(0)
	v_add_f32_e32 v90, v90, v91
	ds_bpermute_b32 v91, v147, v90
	s_waitcnt lgkmcnt(0)
	v_add_f32_e32 v90, v90, v91
	v_fmamk_f32 v90, v90, 0x3c000000, v141
	v_rsq_f32_e32 v90, v90
	s_nop 0
	v_pk_mul_f32 v[94:95], v[90:91], v[124:125] op_sel_hi:[0,1]
	v_pk_mul_f32 v[80:81], v[80:81], v[94:95]
	v_pk_mul_f32 v[94:95], v[90:91], v[120:121] op_sel_hi:[0,1]
	v_pk_mul_f32 v[82:83], v[82:83], v[94:95]
	v_cvt_pk_bf16_f32 v80, v80, v81
	v_cvt_pk_bf16_f32 v81, v82, v83
	v_pk_mul_f32 v[82:83], v[90:91], v[92:93] op_sel_hi:[0,1]
	v_pk_mul_f32 v[82:83], v[84:85], v[82:83]
	v_pk_mul_f32 v[84:85], v[90:91], v[88:89] op_sel_hi:[0,1]
	v_pk_mul_f32 v[84:85], v[86:87], v[84:85]
	v_cvt_pk_bf16_f32 v82, v82, v83
	v_cvt_pk_bf16_f32 v83, v84, v85
	ds_write_b128 v154, v[80:83] offset:57344
	s_waitcnt vmcnt(1)
	ds_write_b128 v157, v[96:99] offset:16384
	s_waitcnt vmcnt(0)
	ds_write_b128 v158, v[100:103] offset:16384
	s_waitcnt lgkmcnt(0)
	s_barrier
	s_nop 0
	v_readfirstlane_b32 s0, v172
	s_nop 0
	s_bitcmp1_b32 s0, 8
	s_cbranch_scc0 .Lstg_1
	s_sleep 8
; #define SLOAD(t) do { const size_t r0_ = (size_t)((t) * 64 + sr) * LD1 + sc; st_k0 = *(const bf16x8*)(Kh + r0_); st_k1 = *(const bf16x8*)(Kh + r0_ + (size_t)32 * LD1); \
;         st_v0 = *(const bf16x8*)(Vh + r0_); st_v1 = *(const bf16x8*)(Vh + r0_ + (size_t)32 * LD1); } while (0)
; #define SWRITE(bf) do { *(bf16x8*)(K_lds + (bf) * SHM_K + kws) = knorm8(st_k0, kgl + sc); *(bf16x8*)(K_lds + (bf) * SHM_K + kws + 32 * 256) = knorm8(st_k1, kgl + sc); \
;         *(bf16x8*)(V_lds + (bf) * SHM_V + vst0) = st_v0; *(bf16x8*)(V_lds + (bf) * SHM_V + vst1) = st_v1; } while (0)
; __device__ __forceinline__ void fox_attn_unit(const Params& P, char* lds, int b, int h, int qb) {
;     ...
;     float m_reg = -1e30f, l_reg = 0.f; f32x16 o[4] = {};
;     __syncthreads();
;     int j_lo; { const float thr = *(const float*)(ws + WS_THR), cq0 = ckl[q0];
;         const bool skip = lane < 4 * qb && ckl[64 * lane + 63] - cq0 > thr; const unsigned long long bm = __ballot(!skip); j_lo = (int)__builtin_ctzll(bm) & ~1; }
;     SLOAD(NT - 1); SWRITE(0);
;     __syncthreads();
;     for (int t = NT - 1; t > j_lo; t -= 2) {
;         SLOAD(t - 1);
;         { const int kb0 = t * 64; fox_tile<0>(o, m_reg, l_reg, lds, ckl, al_l, vb0, qr, cq, qpos, kb0, kb0 + 63 > qlo, r32, hi); }
;         SWRITE(1);
;         __syncthreads();
;         if (t - 2 > j_lo) SLOAD(t - 2);
.Lstg_1:
	s_cbranch_vccnz .LBB0_1343
	v_lshl_add_u64 v[80:81], v[116:117], 0, v[112:113]
	v_add_co_u32_e32 v82, vcc, 0x11401000, v80
	s_nop 1
	v_addc_co_u32_e32 v83, vcc, 0, v81, vcc
	v_add_co_u32_e32 v84, vcc, 0x11481000, v80
	s_nop 1
	v_addc_co_u32_e32 v85, vcc, 0, v81, vcc
	global_load_dwordx4 v[108:111], v[82:83], off
	global_load_dwordx4 v[104:107], v[84:85], off
	v_add_co_u32_e32 v82, vcc, 0x11402000, v80
	s_nop 1
	v_addc_co_u32_e32 v83, vcc, 0, v81, vcc
	v_add_co_u32_e32 v80, vcc, 0x11482000, v80
	s_nop 1
	v_addc_co_u32_e32 v81, vcc, 0, v81, vcc
	global_load_dwordx4 v[96:99], v[82:83], off
	global_load_dwordx4 v[100:103], v[80:81], off

; #define SLOAD(t) do { const size_t r0_ = (size_t)((t) * 64 + sr) * LD1 + sc; st_k0 = *(const bf16x8*)(Kh + r0_); st_k1 = *(const bf16x8*)(Kh + r0_ + (size_t)32 * LD1); \
;         st_v0 = *(const bf16x8*)(Vh + r0_); st_v1 = *(const bf16x8*)(Vh + r0_ + (size_t)32 * LD1); } while (0)
; #define SWRITE(bf) do { *(bf16x8*)(K_lds + (bf) * SHM_K + kws) = knorm8(st_k0, kgl + sc); *(bf16x8*)(K_lds + (bf) * SHM_K + kws + 32 * 256) = knorm8(st_k1, kgl + sc); \
;         *(bf16x8*)(V_lds + (bf) * SHM_V + vst0) = st_v0; *(bf16x8*)(V_lds + (bf) * SHM_V + vst1) = st_v1; } while (0)
; template <int BUF>
; __device__ __forceinline__ void fox_tile(f32x16* o, float& m_reg, float& l_reg, const char* lds, const float* ckl, float* al_l, int vb0, const bf16x8* qr, float cq, int qpos, int kb0, bool need_mask, int r32, int hi) {
;     ...
;     for (int r = 0; r < 16; ++r) { p0[r] = __builtin_amdgcn_exp2f(p0[r] - mn); p1[r] = __builtin_amdgcn_exp2f(p1[r] - mn); ps += p0[r] + p1[r]; }
;     { auto rr = __builtin_amdgcn_permlane32_swap(__float_as_uint(ps), __float_as_uint(ps), false, false); ps = __uint_as_float(rr[0]) + __uint_as_float(rr[1]); }
;     l_reg = l_reg * alpha + ps;
; __device__ __forceinline__ void fox_attn_unit(const Params& P, char* lds, int b, int h, int qb) {
;     ...
;     for (int t = NT - 1; t > j_lo; t -= 2) {
;         SLOAD(t - 1);
;         { const int kb0 = t * 64; fox_tile<0>(o, m_reg, l_reg, lds, ckl, al_l, vb0, qr, cq, qpos, kb0, kb0 + 63 > qlo, r32, hi); }
;         SWRITE(1);
;         __syncthreads();
;         if (t - 2 > j_lo) SLOAD(t - 2);
;         { const int kb0 = (t - 1) * 64; fox_tile<1>(o, m_reg, l_reg, lds, ckl, al_l, vb0, qr, cq, qpos, kb0, kb0 + 63 > qlo, r32, hi); }
;         if (t - 2 > j_lo) SWRITE(0);
;         __syncthreads();
;     }
.LBB0_1365:
	v_add_f32_e32 v80, v167, v168
	v_fmac_f32_e32 v80, v155, v166
	v_add_f32_e32 v155, v121, v122
	v_fmac_f32_e32 v155, v80, v120
	v_lshl_add_u64 v[116:117], v[116:117], 0, s[96:97]
	s_add_i32 s78, s78, -2
	v_add_u32_e32 v160, 0x80, v160
	s_addk_i32 s79, 0xff80
	v_add_u32_e32 v161, 0xfffffe00, v161
	v_lshl_add_u64 v[118:119], v[118:119], 0, s[96:97]
	s_and_b64 vcc, exec, s[2:3]
	s_waitcnt lgkmcnt(0)
	s_barrier
	s_nop 0
	v_readfirstlane_b32 s0, v172
	s_nop 0
	s_bitcmp1_b32 s0, 8
	s_cbranch_scc0 .Lstg_2
	s_sleep 8

; __device__ __forceinline__ unsigned cvtpk(float lo, float hi) { f32x2_t v = {lo, hi}; bf16x2_t b = __builtin_convertvector(v, bf16x2_t); return __builtin_bit_cast(unsigned, b); }
; #define PV_RD(S, d0) do { constexpr int b_ = VB * SHM_V + v_rd_off(d0, 0, 0); \
;         TRRD(S##l0, b_); TRRD(S##h0, b_ + 2048); TRRD(S##l1, b_ + 4096); TRRD(S##h1, b_ + 6144); TRRD(S##l2, b_ + 8192); TRRD(S##h2, b_ + 10240); TRRD(S##l3, b_ + 12288); TRRD(S##h3, b_ + 14336); } while (0)
; #define PV_WAIT(n) do { asm volatile("s_waitcnt lgkmcnt(%0)" :: "i"(n) : "memory"); SBAR(); } while (0)
; template <int VB>
; __device__ __forceinline__ void pv_tile(f32x16* o, int vb0, bf16x8 pa0, bf16x8 pa1, bf16x8 pa2, bf16x8 pa3) {
;     ...
;     s16x4 Al0, Al1, Al2, Al3, Ah0, Ah1, Ah2, Ah3, Bl0, Bl1, Bl2, Bl3, Bh0, Bh1, Bh2, Bh3;
;     PV_RD(A, 0); PV_RD(B, 1); PV_WAIT(8); PV_MM(A, 0);
;     PV_RD(A, 2); PV_WAIT(8); PV_MM(B, 1);
;     PV_RD(B, 3); PV_WAIT(8); PV_MM(A, 2);
;     PV_WAIT(0); PV_MM(B, 3);
; __device__ __forceinline__ bf16x8 knorm8(bf16x8 x, const float* g) {
;     const v4u xv = __builtin_bit_cast(v4u, x); float f[8];
; #pragma unroll
;     for (int e = 0; e < 4; ++e) { f[2 * e] = __builtin_bit_cast(float, xv[e] << 16); f[2 * e + 1] = __builtin_bit_cast(float, xv[e] & 0xffff0000u); }
;     float s = 0.f;
; #pragma unroll
;     for (int e = 0; e < 8; ++e) s += f[e] * f[e];
;     s += __shfl_xor(s, 1); s += __shfl_xor(s, 2); s += __shfl_xor(s, 4); s += __shfl_xor(s, 8);
;     const float r = __builtin_amdgcn_rsqf(s * (1.0f / 128.0f) + 1e-6f);
;     const f32x4 g0 = *(const f32x4*)g, g1 = *(const f32x4*)(g + 4);
;     v4u w; w.x = cvtpk(f[0] * r * g0[0], f[1] * r * g0[1]); w.y = cvtpk(f[2] * r * g0[2], f[3] * r * g0[3]); w.z = cvtpk(f[4] * r * g1[0], f[5] * r * g1[1]); w.w = cvtpk(f[6] * r * g1[2], f[7] * r * g1[3]);
;     return __builtin_bit_cast(bf16x8, w);
.LBB0_1372:
	ds_read_b64_tr_b16 v[120:121], v158 offset:0
	ds_read_b64_tr_b16 v[122:123], v158 offset:0x800
	ds_read_b64_tr_b16 v[124:125], v158 offset:0x1000
	ds_read_b64_tr_b16 v[126:127], v158 offset:0x1800
	ds_read_b64_tr_b16 v[130:131], v158 offset:0x2000
	ds_read_b64_tr_b16 v[132:133], v158 offset:0x2800
	ds_read_b64_tr_b16 v[134:135], v158 offset:0x3000
	ds_read_b64_tr_b16 v[136:137], v158 offset:0x3800
	ds_read_b64_tr_b16 v[178:179], v158 offset:0x200
	ds_read_b64_tr_b16 v[180:181], v158 offset:0xa00
	ds_read_b64_tr_b16 v[182:183], v158 offset:0x1200
	ds_read_b64_tr_b16 v[184:185], v158 offset:0x1a00
	ds_read_b64_tr_b16 v[186:187], v158 offset:0x2200
	ds_read_b64_tr_b16 v[188:189], v158 offset:0x2a00
	ds_read_b64_tr_b16 v[190:191], v158 offset:0x3200
	ds_read_b64_tr_b16 v[192:193], v158 offset:0x3a00
	s_waitcnt lgkmcnt(8)
	s_nop 0
	v_mfma_f32_32x32x16_bf16 v[0:15], v[80:83], v[120:123], v[0:15]
	ds_read_b64_tr_b16 v[120:121], v158 offset:0x400
	ds_read_b64_tr_b16 v[122:123], v158 offset:0xc00
	v_mfma_f32_32x32x16_bf16 v[0:15], v[84:87], v[124:127], v[0:15]
	ds_read_b64_tr_b16 v[124:125], v158 offset:0x1400
	ds_read_b64_tr_b16 v[126:127], v158 offset:0x1c00
	v_mfma_f32_32x32x16_bf16 v[0:15], v[88:91], v[130:133], v[0:15]
	ds_read_b64_tr_b16 v[130:131], v158 offset:0x2400
	ds_read_b64_tr_b16 v[132:133], v158 offset:0x2c00
	v_mfma_f32_32x32x16_bf16 v[0:15], v[92:95], v[134:137], v[0:15]
	ds_read_b64_tr_b16 v[134:135], v158 offset:0x3400
	ds_read_b64_tr_b16 v[136:137], v158 offset:0x3c00
	s_waitcnt lgkmcnt(8)
	v_mfma_f32_32x32x16_bf16 v[32:47], v[80:83], v[178:181], v[32:47]
	ds_read_b64_tr_b16 v[178:179], v158 offset:0x600
	ds_read_b64_tr_b16 v[180:181], v158 offset:0xe00
	v_mfma_f32_32x32x16_bf16 v[32:47], v[84:87], v[182:185], v[32:47]
	ds_read_b64_tr_b16 v[182:183], v158 offset:0x1600
	ds_read_b64_tr_b16 v[184:185], v158 offset:0x1e00
	v_mfma_f32_32x32x16_bf16 v[32:47], v[88:91], v[186:189], v[32:47]
	ds_read_b64_tr_b16 v[186:187], v158 offset:0x2600
	ds_read_b64_tr_b16 v[188:189], v158 offset:0x2e00
	v_mfma_f32_32x32x16_bf16 v[32:47], v[92:95], v[190:193], v[32:47]
	ds_read_b64_tr_b16 v[190:191], v158 offset:0x3600
	ds_read_b64_tr_b16 v[192:193], v158 offset:0x3e00
	s_waitcnt lgkmcnt(8)
	v_mfma_f32_32x32x16_bf16 v[48:63], v[80:83], v[120:123], v[48:63]
	s_waitcnt lgkmcnt(0)
	v_mfma_f32_32x32x16_bf16 v[48:63], v[84:87], v[124:127], v[48:63]
	v_mfma_f32_32x32x16_bf16 v[48:63], v[88:91], v[130:133], v[48:63]
	v_mfma_f32_32x32x16_bf16 v[48:63], v[92:95], v[134:137], v[48:63]
	v_mfma_f32_32x32x16_bf16 v[16:31], v[80:83], v[178:181], v[16:31]
	s_waitcnt vmcnt(3)
	v_lshlrev_b32_e32 v124, 16, v108
	v_and_b32_e32 v125, 0xffff0000, v108
	v_lshlrev_b32_e32 v120, 16, v109
	v_and_b32_e32 v121, 0xffff0000, v109
	v_pk_mul_f32 v[126:127], v[124:125], v[124:125]
	v_pk_mul_f32 v[122:123], v[120:121], v[120:121]
	v_add_f32_e32 v126, v126, v127
	v_mfma_f32_32x32x16_bf16 v[16:31], v[84:87], v[182:185], v[16:31]
	v_add_f32_e32 v122, v122, v126
	v_add_f32_e32 v122, v123, v122
	ds_read_b128 v[80:83], v153
	ds_read_b128 v[84:87], v153 offset:16
	s_cmp_gt_i32 s78, s77
	s_cselect_b64 s[74:75], -1, 0
	s_cmp_le_i32 s78, s77
	s_cselect_b64 s[2:3], -1, 0
	v_mfma_f32_32x32x16_bf16 v[16:31], v[88:91], v[186:189], v[16:31]
	v_lshlrev_b32_e32 v88, 16, v111
	v_and_b32_e32 v89, 0xffff0000, v111
	v_mul_f32_e64 v90, v88, v88
	v_mul_f32_e64 v91, v89, v89
	s_and_b64 vcc, exec, s[2:3]
	v_mfma_f32_32x32x16_bf16 v[16:31], v[92:95], v[190:193], v[16:31]
	v_lshlrev_b32_e32 v92, 16, v110
	v_and_b32_e32 v93, 0xffff0000, v110
	v_mul_f32_e64 v94, v92, v92
	v_mul_f32_e64 v95, v93, v93
	v_add_f32_e32 v94, v94, v122
	v_add_f32_e32 v94, v95, v94
	v_add_f32_e32 v90, v90, v94
	v_add_f32_e32 v90, v91, v90
	ds_bpermute_b32 v91, v144, v90
	s_waitcnt lgkmcnt(0)
	v_add_f32_e32 v90, v90, v91
	ds_bpermute_b32 v91, v145, v90
	s_waitcnt lgkmcnt(0)
	v_add_f32_e32 v90, v90, v91
	ds_bpermute_b32 v91, v146, v90
	s_waitcnt lgkmcnt(0)
	v_add_f32_e32 v90, v90, v91
	ds_bpermute_b32 v91, v147, v90
	s_waitcnt lgkmcnt(0)
	v_add_f32_e32 v90, v90, v91
	v_fmamk_f32 v90, v90, 0x3c000000, v141
	v_rsq_f32_e32 v90, v90
	s_nop 0
	v_pk_mul_f32 v[94:95], v[90:91], v[124:125] op_sel_hi:[0,1]
	s_waitcnt vmcnt(2)
	v_lshlrev_b32_e32 v124, 16, v104
	v_and_b32_e32 v125, 0xffff0000, v104
	v_pk_mul_f32 v[80:81], v[80:81], v[94:95]
	v_pk_mul_f32 v[94:95], v[90:91], v[120:121] op_sel_hi:[0,1]
	v_lshlrev_b32_e32 v120, 16, v105
	v_and_b32_e32 v121, 0xffff0000, v105
	v_pk_mul_f32 v[126:127], v[124:125], v[124:125]
	v_pk_mul_f32 v[82:83], v[82:83], v[94:95]
	v_pk_mul_f32 v[122:123], v[120:121], v[120:121]
	v_add_f32_e32 v126, v126, v127
	v_cvt_pk_bf16_f32 v80, v80, v81
	v_cvt_pk_bf16_f32 v81, v82, v83
	v_pk_mul_f32 v[82:83], v[90:91], v[92:93] op_sel_hi:[0,1]
	v_lshlrev_b32_e32 v92, 16, v106
	v_and_b32_e32 v93, 0xffff0000, v106
	v_add_f32_e32 v122, v122, v126
	v_pk_mul_f32 v[94:95], v[92:93], v[92:93]
	v_add_f32_e32 v122, v123, v122
	v_pk_mul_f32 v[82:83], v[84:85], v[82:83]
	v_pk_mul_f32 v[84:85], v[90:91], v[88:89] op_sel_hi:[0,1]
	v_lshlrev_b32_e32 v88, 16, v107
	v_and_b32_e32 v89, 0xffff0000, v107
	v_add_f32_e32 v94, v94, v122
	v_pk_mul_f32 v[90:91], v[88:89], v[88:89]
	v_add_f32_e32 v94, v95, v94
	v_add_f32_e32 v90, v90, v94
	v_add_f32_e32 v90, v91, v90
	ds_bpermute_b32 v91, v144, v90
	v_pk_mul_f32 v[84:85], v[86:87], v[84:85]
	v_cvt_pk_bf16_f32 v82, v82, v83
	v_cvt_pk_bf16_f32 v83, v84, v85
	ds_write_b128 v154, v[80:83] offset:49152
	s_waitcnt lgkmcnt(1)
	v_add_f32_e32 v90, v90, v91
	ds_bpermute_b32 v91, v145, v90
	ds_read_b128 v[80:83], v153
	ds_read_b128 v[84:87], v153 offset:16
	s_waitcnt lgkmcnt(2)
	v_add_f32_e32 v90, v90, v91
	ds_bpermute_b32 v91, v146, v90
	s_waitcnt lgkmcnt(0)
	v_add_f32_e32 v90, v90, v91
	ds_bpermute_b32 v91, v147, v90
	s_waitcnt lgkmcnt(0)
	v_add_f32_e32 v90, v90, v91
	v_fmamk_f32 v90, v90, 0x3c000000, v141
	v_rsq_f32_e32 v90, v90
	s_nop 0
	v_pk_mul_f32 v[94:95], v[90:91], v[124:125] op_sel_hi:[0,1]
	v_pk_mul_f32 v[80:81], v[80:81], v[94:95]
	v_pk_mul_f32 v[94:95], v[90:91], v[120:121] op_sel_hi:[0,1]
	v_pk_mul_f32 v[82:83], v[82:83], v[94:95]
	v_cvt_pk_bf16_f32 v80, v80, v81
	v_cvt_pk_bf16_f32 v81, v82, v83
	v_pk_mul_f32 v[82:83], v[90:91], v[92:93] op_sel_hi:[0,1]
	v_pk_mul_f32 v[82:83], v[84:85], v[82:83]
	v_pk_mul_f32 v[84:85], v[90:91], v[88:89] op_sel_hi:[0,1]
	v_pk_mul_f32 v[84:85], v[86:87], v[84:85]
	v_cvt_pk_bf16_f32 v82, v82, v83
	v_cvt_pk_bf16_f32 v83, v84, v85
	ds_write_b128 v154, v[80:83] offset:57344
	s_waitcnt vmcnt(1)
	ds_write_b128 v156, v[96:99] offset:16384
	s_waitcnt vmcnt(0)
	ds_write_b128 v157, v[100:103] offset:16384
	s_waitcnt lgkmcnt(0)
	s_barrier
	s_nop 0
	v_readfirstlane_b32 s0, v172
	s_nop 0
	s_bitcmp1_b32 s0, 8
	s_cbranch_scc0 .Lstg_3
	s_sleep 8
